# flattened grid barrier, leader's invalidate issued behind its cross-XCD arrival instead of beside the L2 write-back
# speedup vs baseline: 1.0345x; 1.0030x over previous
.LBB0_860:
	v_readlane_b32 s0, v252, 10
	s_lshl_b32 s50, s0, 2
	v_lshl_add_u64 v[4:5], v[2:3], 0, s[50:51]
	v_add_co_u32_e32 v10, vcc, 0x1000, v4
	v_cvt_f32_u32_e32 v1, v8
	s_nop 0
	v_addc_co_u32_e32 v11, vcc, 0, v5, vcc
	flat_atomic_add v7, v[10:11], v223 offset:1024 sc0
	v_rcp_iflag_f32_e32 v1, v1
	v_sub_u32_e32 v9, 0, v8
	v_mul_f32_e32 v1, 0x4f7ffffe, v1
	v_cvt_u32_f32_e32 v1, v1
	v_mul_lo_u32 v9, v9, v1
	v_mul_hi_u32 v9, v1, v9
	v_add_u32_e32 v1, v1, v9
	s_waitcnt vmcnt(0) lgkmcnt(0)
	v_mul_hi_u32 v1, v7, v1
	v_mul_lo_u32 v9, v1, v8
	v_sub_u32_e32 v9, v7, v9
	v_cmp_ge_u32_e32 vcc, v9, v8
	v_add_u32_e32 v10, 1, v1
	v_add_u32_e32 v7, 1, v7
	v_cndmask_b32_e32 v1, v1, v10, vcc
	v_sub_u32_e32 v10, v9, v8
	v_cndmask_b32_e32 v9, v9, v10, vcc
	v_cmp_ge_u32_e32 vcc, v9, v8
	v_add_u32_e32 v9, 1, v1
	s_nop 0
	v_cndmask_b32_e32 v1, v1, v9, vcc
	v_mad_u64_u32 v[8:9], s[0:1], v8, v1, v[8:9]
	s_mov_b64 s[26:27], 0x3000
	v_add_u32_e32 v9, 1, v1
	v_lshl_add_u64 v[10:11], v[2:3], 0, s[26:27]
	v_mul_lo_u32 v9, v9, v6
	v_cmp_ne_u32_e32 vcc, v7, v8
	s_cbranch_vccnz .Lgb_arrived
	buffer_wbl2 sc1
	s_waitcnt vmcnt(0)
	flat_atomic_add v[10:11], v223 offset:1024
	buffer_inv sc1
	s_branch .Lgb_poll
